# FFN down phase: workgroups with a sample K-slice task run it before their prompt tile, so the two halves' residual epilogues no longer burst together
# speedup vs baseline: 1.0106x; 1.0009x over previous
; __device__ __forceinline__ unsigned xb_ld(unsigned* p)              { return __hip_atomic_load(p, __ATOMIC_RELAXED, __HIP_MEMORY_SCOPE_AGENT); }
; __device__ __forceinline__ unsigned xb_add(unsigned* p, unsigned v) { return __hip_atomic_fetch_add(p, v, __ATOMIC_RELAXED, __HIP_MEMORY_SCOPE_AGENT); }
; #define XB_SPIN(cond, bar) do { unsigned _sp = 0; while (cond) { __builtin_amdgcn_s_sleep(1); \
;     if ((++_sp & 255u) == 0u) { if (xb_ld(&(bar)[XB_TMO])) break; if (_sp > XB_SPIN_CAP) { atomicAdd(&(bar)[XB_TMO], 1u); break; } } } } while (0)
; __device__ __forceinline__ void xcd_barrier_complete(unsigned* bar, unsigned x, unsigned& nloc, unsigned& nx) {
;     const unsigned G = gridDim.x * gridDim.y * gridDim.z;
;     unsigned sum, cnt, mine, sp = 0u;
;     for (;;) {
;         sum = 0u; cnt = 0u; mine = 0u;
; #pragma unroll
;         for (unsigned j = 0; j < 16; ++j) { const unsigned c = xb_ld(&bar[XB_XCNT(j)]); sum += c; cnt += (c > 0u) ? 1u : 0u; mine = (j == x) ? c : mine; }
;         if (sum == G) break;
;         __builtin_amdgcn_s_sleep(1);
;         if ((++sp & 255u) == 0u) { if (xb_ld(&bar[XB_TMO])) break; if (sp > XB_SPIN_CAP) { atomicAdd(&bar[XB_TMO], 1u); break; } }
;     }
;     nloc = mine > 0u ? mine : 1u; nx = cnt > 0u ? cnt : 1u;
; }
; __device__ __forceinline__ void xcd_barrier(const XcdBarrier& b) {
;     asm volatile("s_waitcnt vmcnt(0)" ::: "memory");
;     __syncthreads();
;     if (threadIdx.x == 0) {
;         unsigned* bar = b.bar;
;         __builtin_amdgcn_s_waitcnt(0);
;         unsigned nloc = b.st[0], nx = b.st[1];
;         if (nloc == 0u) { xcd_barrier_complete(bar, b.x, nloc, nx); b.st[0] = nloc; b.st[1] = nx; }
;         const unsigned old = xb_add(&bar[XB_XSUB(b.x)], 1u);
;         const unsigned gen = old / nloc;
;         if (old + 1u == (gen + 1u) * nloc) {
;             __builtin_amdgcn_fence(__ATOMIC_RELEASE, "agent");
;             asm volatile("s_waitcnt vmcnt(0)" ::: "memory");
;             const unsigned og = xb_add(&bar[XB_TOP], 1u);
;             const unsigned tg = og / nx;
;             if (og + 1u == (tg + 1u) * nx) xb_add(&bar[XB_TOPGEN], 1u);
;             else XB_SPIN(xb_ld(&bar[XB_TOPGEN]) == tg, bar);
;             __builtin_amdgcn_fence(__ATOMIC_ACQUIRE, "agent");
;             xb_add(&bar[XB_XGEN(b.x)], 1u);
.LBB0_29:
	s_or_b64 exec, exec, s[4:5]
	s_sub_i32 s70, s50, 64
	s_ashr_i32 s33, s50, 31
	s_lshl_b32 s78, s70, 9
	s_add_u32 s80, s86, 0x21b0200
	s_addc_u32 s81, s87, 0
	s_add_u32 s82, s86, 0x21b0400
	s_addc_u32 s83, s87, 0
	s_add_u32 s46, s86, 0x21b0500
	s_addc_u32 s47, s87, 0
	s_add_u32 s30, s86, 0x21b0600
	s_addc_u32 s31, s87, 0
	s_add_u32 s34, s86, 0x21b0700
	s_mul_i32 s2, s51, s50
	s_addc_u32 s35, s87, 0
	s_mul_i32 s73, s2, s36
	s_add_u32 s2, s86, 0x21b0800
	s_addc_u32 s3, s87, 0
	v_cvt_f32_u32_e32 v0, s78
	v_writelane_b32 v243, s2, 0
	v_cvt_f32_u32_e32 v1, s74
	s_mov_b32 s11, 0
	v_writelane_b32 v243, s3, 1
	s_add_u32 s2, s86, 0x21b0900
	s_addc_u32 s3, s87, 0
	v_writelane_b32 v243, s2, 2
	v_rcp_iflag_f32_e32 v0, v0
	v_rcp_iflag_f32_e32 v1, v1
	v_writelane_b32 v243, s3, 3
	s_add_u32 s2, s86, 0x21b0a00
	s_addc_u32 s3, s87, 0
	v_writelane_b32 v243, s2, 4
	v_mul_f32_e32 v0, 0x4f7ffffe, v0
	v_cvt_u32_f32_e32 v0, v0
	v_writelane_b32 v243, s3, 5
	s_add_u32 s2, s86, 0x21b0b00
	s_addc_u32 s3, s87, 0
	v_writelane_b32 v243, s2, 6
	v_mul_f32_e32 v1, 0x4f7ffffe, v1
	v_cvt_u32_f32_e32 v1, v1
	v_writelane_b32 v243, s3, 7
	s_add_u32 s2, s86, 0x21b0c00
	s_addc_u32 s3, s87, 0
	v_writelane_b32 v243, s2, 8
	s_mov_b32 s79, s78
	s_mov_b32 s75, s74
	v_writelane_b32 v243, s3, 9
	s_add_u32 s2, s86, 0x21b0d00
	s_addc_u32 s3, s87, 0
	v_writelane_b32 v243, s2, 10
	v_mov_b32_e32 v129, 0
	v_mov_b32_e32 v187, 0x358637bd
	v_writelane_b32 v243, s3, 11
	s_add_u32 s2, s86, 0x21b0e00
	s_addc_u32 s3, s87, 0
	v_writelane_b32 v243, s2, 12
	v_mov_b32_e32 v188, 1
	v_mov_b32_e32 v190, 0x3a27c5ac
	v_writelane_b32 v243, s3, 13
	s_add_u32 s2, s86, 0x21b0f00
	s_addc_u32 s3, s87, 0
	v_writelane_b32 v243, s2, 14
	v_mov_b64_e32 v[130:131], 0x43f
	v_mov_b64_e32 v[132:133], 0x440
	v_writelane_b32 v243, s3, 15
	s_add_u32 s2, s86, 0x21b1000
	s_addc_u32 s3, s87, 0
	v_writelane_b32 v243, s2, 16
	v_mov_b64_e32 v[134:135], 0xff
	v_mov_b64_e32 v[136:137], 0x100
	v_writelane_b32 v243, s3, 17
	s_add_u32 s2, s86, 0x21b1100
	s_addc_u32 s3, s87, 0
	v_writelane_b32 v243, s2, 18
	v_mbcnt_hi_u32_b32 v189, -1, v4
	v_mov_b32_e32 v138, 1.0
	v_writelane_b32 v243, s3, 19
	s_add_u32 s2, s86, 0x21b1200
	s_addc_u32 s3, s87, 0
	v_writelane_b32 v243, s2, 20
	v_mov_b32_e32 v191, 3
	v_mov_b64_e32 v[140:141], 0x21f
	v_writelane_b32 v243, s3, 21
	s_add_u32 s2, s86, 0x21b1300
	s_addc_u32 s3, s87, 0
	v_writelane_b32 v243, s2, 22
	s_cmp_eq_u32 s14, 15
	v_mov_b64_e32 v[142:143], 0x220
	v_writelane_b32 v243, s3, 23
	s_cselect_b64 s[2:3], -1, 0
	v_writelane_b32 v243, s2, 24
	s_cmp_eq_u32 s14, 14
	v_mov_b64_e32 v[144:145], 0x1ff
	v_writelane_b32 v243, s3, 25
	s_cselect_b64 s[2:3], -1, 0
	v_writelane_b32 v243, s2, 26
	s_cmp_eq_u32 s14, 13
	v_mov_b64_e32 v[146:147], 0x200
	v_writelane_b32 v243, s3, 27
	s_cselect_b64 s[2:3], -1, 0
	v_writelane_b32 v243, s2, 28
	s_cmp_eq_u32 s14, 12
	s_mov_b32 s67, 0x800000
	v_writelane_b32 v243, s3, 29
	s_cselect_b64 s[2:3], -1, 0
	v_writelane_b32 v243, s2, 30
	s_cmp_eq_u32 s14, 11
	s_movk_i32 s68, 0x5c80
	v_writelane_b32 v243, s3, 31
	s_cselect_b64 s[2:3], -1, 0
	v_writelane_b32 v243, s2, 32
	s_cmp_eq_u32 s14, 10
	s_movk_i32 s69, 0x7fff
	v_writelane_b32 v243, s3, 33
	s_cselect_b64 s[2:3], -1, 0
	v_writelane_b32 v243, s2, 34
	s_cmp_eq_u32 s14, 9
	s_movk_i32 s77, 0xa0
	v_writelane_b32 v243, s3, 35
	s_cselect_b64 s[2:3], -1, 0
	v_writelane_b32 v243, s2, 36
	s_cmp_eq_u32 s14, 8
	s_movk_i32 s58, 0xff60
	v_writelane_b32 v243, s3, 37
	s_cselect_b64 s[2:3], -1, 0
	v_writelane_b32 v243, s2, 38
	s_cmp_eq_u32 s14, 7
	s_mov_b32 s38, 0x1ffff
	v_writelane_b32 v243, s3, 39
	s_cselect_b64 s[2:3], -1, 0
; __device__ __forceinline__ unsigned xb_ld(unsigned* p)              { return __hip_atomic_load(p, __ATOMIC_RELAXED, __HIP_MEMORY_SCOPE_AGENT); }
; __device__ __forceinline__ unsigned xb_add(unsigned* p, unsigned v) { return __hip_atomic_fetch_add(p, v, __ATOMIC_RELAXED, __HIP_MEMORY_SCOPE_AGENT); }
; #define XB_SPIN(cond, bar) do { unsigned _sp = 0; while (cond) { __builtin_amdgcn_s_sleep(1); \
;     if ((++_sp & 255u) == 0u) { if (xb_ld(&(bar)[XB_TMO])) break; if (_sp > XB_SPIN_CAP) { atomicAdd(&(bar)[XB_TMO], 1u); break; } } } } while (0)
; __device__ __forceinline__ void xcd_barrier(const XcdBarrier& b) {
;     asm volatile("s_waitcnt vmcnt(0)" ::: "memory");
;     __syncthreads();
;     if (threadIdx.x == 0) {
;         unsigned* bar = b.bar;
;         __builtin_amdgcn_s_waitcnt(0);
;         unsigned nloc = b.st[0], nx = b.st[1];
;         if (nloc == 0u) { xcd_barrier_complete(bar, b.x, nloc, nx); b.st[0] = nloc; b.st[1] = nx; }
;         const unsigned old = xb_add(&bar[XB_XSUB(b.x)], 1u);
;         const unsigned gen = old / nloc;
;         if (old + 1u == (gen + 1u) * nloc) {
;             __builtin_amdgcn_fence(__ATOMIC_RELEASE, "agent");
;             asm volatile("s_waitcnt vmcnt(0)" ::: "memory");
;             const unsigned og = xb_add(&bar[XB_TOP], 1u);
;             const unsigned tg = og / nx;
;             if (og + 1u == (tg + 1u) * nx) xb_add(&bar[XB_TOPGEN], 1u);
;             else XB_SPIN(xb_ld(&bar[XB_TOPGEN]) == tg, bar);
;             __builtin_amdgcn_fence(__ATOMIC_ACQUIRE, "agent");
;             xb_add(&bar[XB_XGEN(b.x)], 1u);
	v_writelane_b32 v243, s2, 40
	s_cmp_eq_u32 s14, 6
	s_movk_i32 s71, 0x3000
	v_writelane_b32 v243, s3, 41
	s_cselect_b64 s[2:3], -1, 0
	v_writelane_b32 v243, s2, 42
	s_cmp_eq_u32 s14, 5
	s_mov_b32 s72, 0x5040100
	v_writelane_b32 v243, s3, 43
	s_cselect_b64 s[2:3], -1, 0
	v_writelane_b32 v243, s2, 44
	s_cmp_eq_u32 s14, 4
	s_mov_b32 s10, 0x1000000
	v_writelane_b32 v243, s3, 45
	s_cselect_b64 s[2:3], -1, 0
	v_writelane_b32 v243, s2, 46
	s_cmp_eq_u32 s14, 3
	s_mov_b32 s62, 0x1800000
	v_writelane_b32 v243, s3, 47
	s_cselect_b64 s[2:3], -1, 0
	v_writelane_b32 v243, s2, 48
	s_cmp_eq_u32 s14, 2
	s_mov_b64 s[18:19], 0x80
	v_writelane_b32 v243, s3, 49
	s_cselect_b64 s[2:3], -1, 0
	v_writelane_b32 v243, s2, 50
	s_cmp_eq_u32 s14, 1
	s_mov_b64 s[8:9], 0x3000
	v_writelane_b32 v243, s3, 51
	s_cselect_b64 s[2:3], -1, 0
	v_writelane_b32 v243, s2, 52
	s_cmp_eq_u32 s14, 0
	s_mov_b64 s[54:55], 0x400
	v_writelane_b32 v243, s3, 53
	s_cselect_b64 s[2:3], -1, 0
	v_writelane_b32 v243, s2, 54
	s_mov_b32 s28, 0x3f1b4598
	s_nop 0
	v_writelane_b32 v243, s3, 55
	s_lshl_b32 s2, s14, 8
	s_add_u32 s0, s0, s2
	s_addc_u32 s1, s1, 0
	s_add_u32 s2, s0, 0x1400
	s_addc_u32 s3, s1, 0
	v_writelane_b32 v243, s2, 56
	s_add_u32 s0, s0, 0x2400
	s_addc_u32 s1, s1, 0
	v_writelane_b32 v243, s3, 57
	v_writelane_b32 v243, s0, 58
	s_nop 1
	v_writelane_b32 v243, s1, 59
	s_add_u32 s0, s86, 0x21b3400
	s_addc_u32 s1, s87, 0
	v_writelane_b32 v243, s0, 60
	s_nop 1
	v_writelane_b32 v243, s1, 61
	s_add_u32 s0, s86, 0x21b3500
	s_addc_u32 s1, s87, 0
	v_writelane_b32 v243, s0, 62
	s_lshl_b32 s66, s50, 3
	s_lshl_b32 s52, s50, 1
	v_writelane_b32 v243, s1, 63
	s_sub_i32 s51, s50, 32
	s_lshl_b32 s0, s50, 2
	v_writelane_b32 v242, s0, 0
	s_add_u32 s0, s84, 0x45f9200
	s_addc_u32 s1, s85, 0
	v_writelane_b32 v242, s0, 1
	s_lshl_b32 s29, s70, 10
	s_lshl_b32 s39, s50, 12
	v_writelane_b32 v242, s1, 2
	s_sub_i32 s0, 0, s78
	v_mul_lo_u32 v2, s0, v0
	s_sub_i32 s0, 0, s74
	v_mul_lo_u32 v3, s0, v1
	s_mov_b32 s1, -1
	s_mov_b32 s0, s11
	s_and_b64 s[2:3], s[78:79], s[0:1]
	v_writelane_b32 v242, s2, 3
	s_and_b64 s[0:1], s[74:75], s[0:1]
	s_ashr_i32 s79, s78, 31
	v_writelane_b32 v242, s3, 4
	v_writelane_b32 v242, s0, 5
	s_ashr_i32 s75, s74, 31
	v_mul_hi_u32 v2, v0, v2
	v_writelane_b32 v242, s1, 6
	s_add_i32 s0, s74, 0xffff0000
	v_writelane_b32 v242, s0, 7
	v_writelane_b32 v242, s29, 8
	s_lshl_b32 s0, s50, 10
	v_writelane_b32 v242, s0, 9
	v_writelane_b32 v242, s0, 10
	s_lshl_b32 s0, s50, 6
	v_writelane_b32 v242, s0, 11
	s_lshl_b32 s0, s50, 7
	v_writelane_b32 v242, s0, 12
	s_lshl_b32 s0, s50, 5
	v_writelane_b32 v242, s0, 13
	s_lshl_b32 s0, s50, 8
	v_writelane_b32 v242, s0, 14
	s_lshl_b32 s0, s50, 15
	v_writelane_b32 v242, s0, 15
	s_add_i32 s0, 0, 0x20000
	v_writelane_b32 v242, s0, 16
	s_add_i32 s0, 0, 0x20004
	v_writelane_b32 v242, s0, 17
	s_add_i32 s0, 0, 0x1ca00
	v_writelane_b32 v242, s0, 18
	s_mov_b32 s0, 0
	v_writelane_b32 v242, s0, 19
	v_writelane_b32 v242, s0, 61
	s_lshl_b64 s[0:1], s[78:79], 4
	v_writelane_b32 v242, s0, 20
	v_add_u32_e32 v185, v0, v2
	v_mul_hi_u32 v0, v1, v3
	v_writelane_b32 v242, s1, 21
	s_lshl_b64 s[0:1], s[74:75], 4
	v_writelane_b32 v242, s0, 22
	v_add_u32_e32 v186, v1, v0
	s_nop 0
	v_writelane_b32 v242, s1, 23
	v_writelane_b32 v242, s46, 24
	s_nop 1
	v_writelane_b32 v242, s47, 25
	v_writelane_b32 v242, s52, 26
	v_writelane_b32 v242, s29, 27
	v_writelane_b32 v242, s39, 28
	v_writelane_b32 v242, s78, 29
	s_nop 1
	v_writelane_b32 v242, s79, 30
	v_writelane_b32 v242, s30, 31
	s_nop 1
	v_writelane_b32 v242, s31, 32
	v_writelane_b32 v242, s34, 33
	s_nop 1
	v_writelane_b32 v242, s35, 34
	s_branch .LBB0_32

; #define PG8_WAIT_V(n) asm volatile("s_waitcnt vmcnt(" #n ")" ::: "memory")
; template <class Epi, class Sched, bool STAMP = false>
; __device__ __forceinline__ void gemm_phase(PG8_LAS unsigned char* lds, const Gemm g, const Sched& S, const Epi& E, unsigned long long* stamps) {
;     ...
;     for (int i = 0; i < 2; ++i) { int R, C; stage_rc(tid * 16 + i * 8192, R, C); const int Rb = Epi::PERM ? ((R & ~31) + perm32(R & 31)) : R;
;         voffA[i] = (unsigned)(R * LD + C) * 2u; voffB[i] = (unsigned)(Rb * LD + C) * 2u; }
;     const size_t kstep = (size_t)(BK * 2);
;     const size_t hstep = (size_t)HALF * LD * 2;
;     const size_t tstep = 2 * hstep;
;     const unsigned ldsw = (unsigned)wid * 1024u;
;     const int aoff = lds_byte(wr * 64 + fr, fq * 8), boff = lds_byte(wc * 32 + fr, fq * 8);
;     ...
;     Unit cur, nxt; int ui = 0;
;     if (!S.next(0, cur)) return;
;     f32x4 acc[2][2][4][2];
; #pragma unroll
;     for (int a = 0; a < 2; ++a)
; #pragma unroll
;         for (int b = 0; b < 2; ++b)
; #pragma unroll
;             for (int m = 0; m < 4; ++m)
; #pragma unroll
;                 for (int n = 0; n < 2; ++n) acc[a][b][m][n] = (f32x4){0.f, 0.f, 0.f, 0.f};
;     bf16x8 At[4][2], B0[2][2], B1[2][2];
;     const char* cA = (const char*)g.A + (size_t)cur.pm * tstep; const char* cB = (const char*)g.Bt + (size_t)cur.pn * tstep;
;     S.a_ready(cur);
;     PG8_STAGE(PG8_SB(0, 0), cB, voffB); PG8_STAGE(PG8_SA(0, 0), cA, voffA); PG8_STAGE(PG8_SB(0, 1), cB + hstep, voffB); PG8_STAGE(PG8_SA(0, 1), cA + hstep, voffA);
;     if (wr == 1) PG8_BAR;
;     PG8_WAIT_V(4); PG8_BAR;
; __device__ __forceinline__ void run_ffn_down(LAS unsigned char* lds, const bf16_t* HID, const bf16_t* WDN, const EpiResid& E, float* PART) {
;     { pg8::StaticOrder S; S.init(T_P, 1024, (int)gridDim.x, bidx());
;       pg8::Gemm g; g.A = HID; g.Bt = WDN; g.M = T_P; g.N = 1024; g.K = 4096; g.ld = 4096;
;       pg8::gemm_phase<EpiResid, pg8::StaticOrder, false>(lds, g, S, E, nullptr); }
;     { const int t = bidx(); OneUnit S; S.valid = t < 128; const int sl = t & 7, u = (t >> 3) & 15; S.pm = 64 + (u >> 2); S.pn = u & 3;
;       pg8::Gemm g; g.A = HID + sl * 512; g.Bt = WDN + sl * 512; g.M = T_ALL; g.N = 1024; g.K = 512; g.ld = 4096;
;       EpiPartial EA; EA.PART = PART + (size_t)sl * 1024 * 1024; EA.ldp = 1024;
;       pg8::gemm_phase<EpiPartial, OneUnit, false>(lds, g, S, EA, nullptr); }
.LBB0_1171:
	s_add_u32 s45, s10, 0x5500000
	s_addc_u32 s46, s42, 0
	s_add_u32 s47, s10, 0x1800000
	s_addc_u32 s48, s42, 0
	s_cmpk_gt_i32 s90, 0x7f
	s_cbranch_scc1 .Lp13_main
	v_writelane_b32 v255, s0, 0
	v_writelane_b32 v255, s1, 1
	v_writelane_b32 v255, s12, 2
	v_writelane_b32 v255, s13, 3
	v_writelane_b32 v255, s20, 4
	v_writelane_b32 v255, s21, 5
	v_writelane_b32 v255, s22, 6
	v_writelane_b32 v255, s24, 7
	v_writelane_b32 v255, s34, 8
	v_writelane_b32 v255, s35, 9
	s_mov_b32 s0, 1
	v_writelane_b32 v242, s0, 61
	s_branch .LBB0_1203
.Lp13_back:
	s_mov_b32 s0, 2
	v_writelane_b32 v242, s0, 61
	v_readlane_b32 s0, v255, 0
	v_readlane_b32 s1, v255, 1
	v_readlane_b32 s12, v255, 2
	v_readlane_b32 s13, v255, 3
	v_readlane_b32 s20, v255, 4
	v_readlane_b32 s21, v255, 5
	v_readlane_b32 s22, v255, 6
	v_readlane_b32 s24, v255, 7
	v_readlane_b32 s34, v255, 8
	v_readlane_b32 s35, v255, 9
	v_mov_b32_e32 v9, v184
	s_branch .Lp13_main
.Lp13_skipB:
	s_mov_b32 s4, 0
	v_writelane_b32 v242, s4, 61
	s_branch .LBB0_1211
.Lp13_main:
	s_andn2_b64 vcc, exec, s[0:1]
	s_cbranch_vccnz .LBB0_1203
	v_ashrrev_i32_e32 v1, 31, v9
	v_lshrrev_b32_e32 v1, 26, v1
	v_add_u32_e32 v1, v9, v1
	v_ashrrev_i32_e32 v8, 6, v1
	v_bfe_i32 v1, v9, 27, 1
	v_lshlrev_b32_e32 v0, 4, v9
	v_lshrrev_b32_e32 v1, 22, v1
	v_add_u32_e32 v1, v0, v1
	v_and_b32_e32 v1, 0xfffffc00, v1
	v_sub_u32_e32 v1, v0, v1
	v_lshrrev_b32_e32 v2, 4, v1
	v_bitop3_b32 v1, v2, v1, 32 bitop3:0x6c
	v_ashrrev_i32_e32 v3, 31, v1
	v_lshrrev_b32_e32 v3, 26, v3
	v_add_u32_e32 v3, v1, v3
	v_lshlrev_b32_e32 v2, 3, v8
	v_ashrrev_i32_e32 v10, 6, v3
	v_and_b32_e32 v3, 0xc0, v3
	v_and_b32_e32 v2, 0x7fff0, v2
	v_lshlrev_b32_e32 v4, 5, v8
	v_sub_u32_e32 v1, v1, v3
	v_add_u32_e32 v2, v10, v2
	v_and_b32_e32 v11, 32, v4
	v_ashrrev_i16_sdwa v1, v188, sext(v1) dst_sel:DWORD dst_unused:UNUSED_PAD src0_sel:DWORD src1_sel:BYTE_0
	s_waitcnt lgkmcnt(0)
	v_bfe_i32 v12, v1, 0, 16
	v_lshl_or_b32 v1, v2, 12, v11
	v_add_u32_e32 v0, 0x2000, v0
	v_add_lshl_u32 v128, v1, v12, 1
	v_ashrrev_i32_e32 v1, 31, v0
	v_lshrrev_b32_e32 v1, 22, v1
	v_add_u32_e32 v1, v0, v1
	v_ashrrev_i32_e32 v13, 10, v1
	v_mul_i32_i24_e32 v1, 0x400, v13
	v_sub_u32_e32 v0, v0, v1
	v_lshrrev_b32_e32 v1, 4, v0
	v_bitop3_b32 v0, v1, v0, 32 bitop3:0x6c
	v_ashrrev_i32_e32 v2, 31, v0
	v_lshrrev_b32_e32 v2, 26, v2
	s_ashr_i32 s5, s44, 6
	s_ashr_i32 s23, s22, 31
	s_ashr_i32 s25, s24, 31
	s_ashr_i32 s4, s44, 8
	v_add_u32_e32 v2, v0, v2
	s_lshl_b32 s49, s5, 10
	s_lshl_b64 s[0:1], s[22:23], 21
	s_lshl_b64 s[2:3], s[24:25], 21
	v_lshlrev_b32_e32 v1, 3, v13
	v_ashrrev_i32_e32 v14, 6, v2
	v_and_b32_e32 v2, 0xc0, v2
	s_add_u32 s30, s47, s2
	v_and_b32_e32 v1, 0x7fff0, v1
	v_lshlrev_b32_e32 v3, 5, v13
	v_sub_u32_e32 v0, v0, v2
	s_addc_u32 s31, s48, s3
	s_add_i32 s25, s49, 0
	v_add_u32_e32 v1, v14, v1
	v_and_b32_e32 v15, 32, v3
	v_ashrrev_i16_sdwa v0, v188, sext(v0) dst_sel:DWORD dst_unused:UNUSED_PAD src0_sel:DWORD src1_sel:BYTE_0
	s_add_i32 m0, s25, 0x10000
	v_bfe_i32 v16, v0, 0, 16
	v_lshl_or_b32 v0, v1, 12, v15
	global_load_lds_dwordx4 v128, s[30:31]
	s_add_i32 m0, s25, 0x12000
	v_add_lshl_u32 v148, v0, v16, 1
	s_add_u32 s26, s45, s0
	global_load_lds_dwordx4 v148, s[30:31]
	s_addc_u32 s27, s46, s1
	s_mov_b32 m0, s25
	s_add_i32 s53, s25, 0x2000
	global_load_lds_dwordx4 v128, s[26:27]
	s_mov_b32 m0, s53
	s_add_u32 s0, s30, 0x100000
	global_load_lds_dwordx4 v148, s[26:27]
	s_addc_u32 s1, s31, 0
	s_add_i32 m0, s25, 0x14000
	v_mov_b32_e32 v149, v129
	global_load_lds_dwordx4 v128, s[0:1]
	s_add_i32 m0, s25, 0x16000
	v_lshl_add_u64 v[6:7], s[30:31], 0, v[128:129]
	global_load_lds_dwordx4 v148, s[0:1]
	s_add_u32 s0, s26, 0x100000
	s_addc_u32 s1, s27, 0
	s_add_i32 s56, s25, 0x4000
	s_mov_b32 m0, s56
	s_add_i32 s57, s25, 0x6000
	global_load_lds_dwordx4 v128, s[0:1]
	s_mov_b32 m0, s57
	v_lshl_add_u64 v[4:5], s[30:31], 0, v[148:149]
	global_load_lds_dwordx4 v148, s[0:1]
	v_lshl_add_u64 v[2:3], s[26:27], 0, v[128:129]
	s_cmp_lg_u32 s4, 1
	v_lshl_add_u64 v[0:1], s[26:27], 0, v[148:149]
	s_cbranch_scc1 .LBB0_1174
	s_barrier

; __device__ __forceinline__ int bidx() { int b = blockIdx.x; asm volatile("" : "+s"(b)); return b; }
; template <class Epi, class Sched, bool STAMP = false>
; __device__ __forceinline__ void gemm_phase(PG8_LAS unsigned char* lds, const Gemm g, const Sched& S, const Epi& E, unsigned long long* stamps) {
;     ...
;     for (int i = 0; i < 2; ++i) { int R, C; stage_rc(tid * 16 + i * 8192, R, C); const int Rb = Epi::PERM ? ((R & ~31) + perm32(R & 31)) : R;
;         voffA[i] = (unsigned)(R * LD + C) * 2u; voffB[i] = (unsigned)(Rb * LD + C) * 2u; }
; __device__ __forceinline__ void run_ffn_down(LAS unsigned char* lds, const bf16_t* HID, const bf16_t* WDN, const EpiResid& E, float* PART) {
;     ...
;     { const int t = bidx(); OneUnit S; S.valid = t < 128; const int sl = t & 7, u = (t >> 3) & 15; S.pm = 64 + (u >> 2); S.pn = u & 3;
;       pg8::Gemm g; g.A = HID + sl * 512; g.Bt = WDN + sl * 512; g.M = T_ALL; g.N = 1024; g.K = 512; g.ld = 4096;
;       EpiPartial EA; EA.PART = PART + (size_t)sl * 1024 * 1024; EA.ldp = 1024;
;       pg8::gemm_phase<EpiPartial, OneUnit, false>(lds, g, S, EA, nullptr); }
.LBB0_1203:
	v_readlane_b32 s4, v242, 61
	s_cmp_eq_u32 s4, 2
	s_cbranch_scc1 .Lp13_skipB
	s_mov_b32 s4, s90
	s_waitcnt lgkmcnt(0)
	v_mov_b32_e32 v12, v184
	s_cmpk_gt_i32 s4, 0x7f
	s_nop 0
	v_readfirstlane_b32 s22, v12
	s_cbranch_scc1 .LBB0_1211
	v_lshlrev_b32_e32 v0, 4, v12
	v_add_u32_e32 v1, 0x2000, v0
	v_ashrrev_i32_e32 v2, 31, v1
	v_lshrrev_b32_e32 v2, 22, v2
	v_add_u32_e32 v2, v1, v2
	v_ashrrev_i32_e32 v8, 10, v2
	v_mul_i32_i24_e32 v2, 0x400, v8
	v_sub_u32_e32 v1, v1, v2
	v_lshrrev_b32_e32 v2, 4, v1
	v_bitop3_b32 v1, v2, v1, 32 bitop3:0x6c
	v_ashrrev_i32_e32 v2, 31, v1
	v_lshrrev_b32_e32 v2, 26, v2
	v_add_u32_e32 v2, v1, v2
	v_ashrrev_i32_e32 v9, 6, v2
	v_and_b32_e32 v2, 0xc0, v2
	v_sub_u32_e32 v1, v1, v2
	v_ashrrev_i16_sdwa v1, v188, sext(v1) dst_sel:DWORD dst_unused:UNUSED_PAD src0_sel:DWORD src1_sel:BYTE_0
	v_bfe_i32 v11, v1, 0, 16
	v_bfe_i32 v1, v12, 27, 1
	v_lshrrev_b32_e32 v1, 22, v1
	v_add_u32_e32 v1, v0, v1
	v_and_b32_e32 v1, 0xfffffc00, v1
	v_sub_u32_e32 v0, v0, v1
	v_lshrrev_b32_e32 v1, 4, v0
	s_and_b32 s25, s4, 7
	s_bfe_u32 s0, s4, 0x20005
	s_ashr_i32 s6, s22, 6
	v_bitop3_b32 v0, v1, v0, 32 bitop3:0x6c
	v_ashrrev_i32_e32 v2, 31, v12
	s_or_b32 s24, s0, 64
	s_bfe_u32 s23, s4, 0x20003
	s_ashr_i32 s7, s22, 8
	s_lshl_b32 s26, s6, 10
	s_lshl_b32 s5, s25, 10
	v_lshlrev_b32_e32 v3, 3, v8
	v_ashrrev_i32_e32 v1, 31, v0
	v_lshrrev_b32_e32 v2, 26, v2
	s_add_u32 s0, s47, s5
	v_and_b32_e32 v3, 0x7fff0, v3
	v_lshlrev_b32_e32 v4, 5, v8
	v_lshrrev_b32_e32 v1, 26, v1
	v_add_u32_e32 v2, v12, v2
	s_addc_u32 s1, s48, 0
	v_add_u32_e32 v3, v9, v3
	v_and_b32_e32 v10, 32, v4
	v_add_u32_e32 v1, v0, v1
	v_ashrrev_i32_e32 v14, 6, v2
	s_add_u32 s2, s45, s5
	v_lshl_or_b32 v3, v3, 12, v10
	v_ashrrev_i32_e32 v13, 6, v1
	v_lshlrev_b32_e32 v2, 3, v14
	v_and_b32_e32 v1, 0xc0, v1
	s_addc_u32 s3, s46, 0
	v_add_lshl_u32 v148, v3, v11, 1
	v_and_b32_e32 v2, 0x7fff0, v2
	v_lshlrev_b32_e32 v3, 5, v14
	v_sub_u32_e32 v0, v0, v1
	s_lshl_b32 s12, s24, 21
	s_lshl_b32 s13, s23, 21
	v_add_u32_e32 v2, v13, v2
	v_and_b32_e32 v15, 32, v3
	v_ashrrev_i16_sdwa v0, v188, sext(v0) dst_sel:DWORD dst_unused:UNUSED_PAD src0_sel:DWORD src1_sel:BYTE_0
	s_add_u32 s0, s0, s13
	v_lshl_or_b32 v2, v2, 12, v15
	v_bfe_i32 v16, v0, 0, 16
	s_addc_u32 s1, s1, 0
	s_add_i32 s27, s26, 0
	v_add_lshl_u32 v128, v2, v16, 1
	s_add_i32 m0, s27, 0x10000
	v_mov_b32_e32 v149, v129
	global_load_lds_dwordx4 v128, s[0:1]
	s_add_i32 m0, s27, 0x12000
	s_add_u32 s2, s2, s12
	global_load_lds_dwordx4 v148, s[0:1]
	s_addc_u32 s3, s3, 0
	s_mov_b32 m0, s27
	s_add_i32 s30, s27, 0x2000
	global_load_lds_dwordx4 v128, s[2:3]
	s_mov_b32 m0, s30
	s_add_u32 s12, s0, 0x100000
	global_load_lds_dwordx4 v148, s[2:3]
	s_addc_u32 s13, s1, 0
	s_add_i32 m0, s27, 0x14000
	v_lshl_add_u64 v[6:7], s[0:1], 0, v[128:129]
	global_load_lds_dwordx4 v128, s[12:13]
	s_add_i32 m0, s27, 0x16000
	v_lshl_add_u64 v[4:5], s[0:1], 0, v[148:149]
	global_load_lds_dwordx4 v148, s[12:13]
	s_add_u32 s12, s2, 0x100000
	s_addc_u32 s13, s3, 0
	s_add_i32 s31, s27, 0x4000
	s_mov_b32 m0, s31
	s_add_i32 s34, s27, 0x6000
	global_load_lds_dwordx4 v128, s[12:13]
	s_mov_b32 m0, s34
	v_lshl_add_u64 v[2:3], s[2:3], 0, v[128:129]
	global_load_lds_dwordx4 v148, s[12:13]
	s_cmp_lg_u32 s7, 1
	v_lshl_add_u64 v[0:1], s[2:3], 0, v[148:149]
	s_cbranch_scc1 .LBB0_1206
	s_barrier

; __global__ void __launch_bounds__(512, 2) mega_fwd(Params prm) {
;     ...
;         default: { GEMM_PRO; EpiResid E; E.X = p.out; E.XB = XB; E.rowss_out = rs_next; E.Xp0 = nullptr; E.Xs0 = nullptr; run_ffn_down(lds, (const bf16_t*)(ws + OFF_A), (const bf16_t*)(ws + OFF_WDN), E, (float*)(ws + OFF_PART)); } break;
;         }
;         xcd_barrier(xb);
.LBB0_1211:
	v_readlane_b32 s36, v242, 61
	s_cmp_eq_u32 s36, 1
	s_cbranch_scc1 .Lp13_back
	v_readlane_b32 s46, v242, 24
	s_mov_b64 s[36:37], 0
	s_mov_b64 s[0:1], s[88:89]
	v_readlane_b32 s47, v242, 25
	s_mov_b32 s10, 0x1000000
